# plus P0/P4 row loops: loop-top vmcnt drain moved to the entry path so the next-row prefetch does not wait for store acks
# speedup vs baseline: 1.0334x; 1.0149x over previous
; #define LAS __attribute__((address_space(3)))
; __device__ __forceinline__ void phase0(const Params& P, LAS unsigned char* lds, int tid, int lane, int wave) {
;     ...
;     f32x4 g4[4];
; #pragma unroll
;     for (int j = 0; j < 4; ++j) g4[j] = *(const f32x4*)(P.gain + 4 * lane + 256 * j);
;     const float bfv = P.bfg[lane & 7];
;     f32x4 nv[4];
;     if (gw < MT) {
;         const float* xrow = (gw < MP) ? P.xp + (size_t)gw * 1024 : P.xs + (size_t)(gw - MP) * 1024;
; #pragma unroll
;         for (int j = 0; j < 4; ++j) nv[j] = *(const f32x4*)(xrow + 4 * lane + 256 * j);
;     }
;     ...
;             for (int e = 0; e < 4; ++e) {
;                 const int k = 4 * lane + 256 * j + e;
;                 const f32x4 w0 = *(const LAS f32x4*)(wfL + k * 8), w1 = *(const LAS f32x4*)(wfL + k * 8 + 4);
.LBB0_28:
	v_readlane_b32 s0, v241, 10
	v_readlane_b32 s1, v241, 11
	s_cmp_lt_i32 s0, 0x10100
	s_cselect_b64 s[0:1], -1, 0
	v_writelane_b32 v241, s0, 12
	s_mov_b64 s[6:7], s[38:39]
	s_mov_b64 s[8:9], s[40:41]
	v_writelane_b32 v241, s1, 13
	v_writelane_b32 v241, s4, 14
	s_and_b64 vcc, exec, s[0:1]
	v_mbcnt_lo_u32_b32 v179, -1, 0
	v_writelane_b32 v241, s5, 15
	v_writelane_b32 v241, s6, 16
	v_writelane_b32 v241, s7, 17
	v_writelane_b32 v241, s8, 18
	v_writelane_b32 v241, s9, 19
	v_writelane_b32 v241, s10, 20
	s_waitcnt lgkmcnt(0)
	s_barrier
	v_writelane_b32 v241, s11, 21
	s_cbranch_vccz .LBB0_35
	v_readlane_b32 s24, v241, 10
	v_readlane_b32 s25, v241, 11
	s_add_i32 s3, s24, 0xffff0000
	s_ashr_i32 s25, s24, 31
	s_cmp_lt_i32 s24, 0x10000
	s_cselect_b32 s1, s25, 0
	s_cselect_b32 s0, s24, s3
	s_cselect_b32 s4, s69, s71
	s_cselect_b32 s5, s68, s70
	s_lshl_b64 s[0:1], s[0:1], 12
	s_add_u32 s0, s5, s0
	v_lshlrev_b32_e32 v18, 4, v146
	v_lshlrev_b32_e32 v1, 2, v19
	s_addc_u32 s1, s4, s1
	global_load_dwordx4 v[2:5], v18, s[82:83]
	global_load_dwordx4 v[6:9], v18, s[82:83] offset:1024
	global_load_dwordx4 v[10:13], v18, s[82:83] offset:2048
	global_load_dwordx4 v[14:17], v18, s[82:83] offset:3072
	s_ashr_i32 s85, s84, 31
	global_load_dword v1, v1, s[38:39]
	s_nop 0
	global_load_dwordx4 v[174:177], v18, s[0:1]
	global_load_dwordx4 v[170:173], v18, s[0:1] offset:1024
	global_load_dwordx4 v[166:169], v18, s[0:1] offset:2048
	global_load_dwordx4 v[162:165], v18, s[0:1] offset:3072
	v_mbcnt_hi_u32_b32 v18, -1, v179
	v_and_b32_e32 v19, 64, v18
	v_add_u32_e32 v19, 64, v19
	v_xor_b32_e32 v20, 1, v18
	v_cmp_lt_i32_e32 vcc, v20, v19
	s_lshl_b64 s[18:19], s[24:25], 11
	s_add_u32 s18, s92, s18
	v_cndmask_b32_e32 v20, v18, v20, vcc
	v_lshlrev_b32_e32 v185, 2, v20
	v_xor_b32_e32 v20, 2, v18
	v_cmp_lt_i32_e32 vcc, v20, v19
	v_lshlrev_b32_e32 v26, 2, v146
	v_mov_b32_e32 v29, 0
	v_cndmask_b32_e32 v20, v18, v20, vcc
	v_lshlrev_b32_e32 v186, 2, v20
	v_xor_b32_e32 v20, 4, v18
	v_cmp_lt_i32_e32 vcc, v20, v19
	v_lshlrev_b32_e32 v28, 3, v146
	s_addc_u32 s19, s93, s19
	v_cndmask_b32_e32 v20, v18, v20, vcc
	v_lshlrev_b32_e32 v187, 2, v20
	v_xor_b32_e32 v20, 8, v18
	v_cmp_lt_i32_e32 vcc, v20, v19
	v_lshl_add_u64 v[28:29], s[18:19], 0, v[28:29]
	s_mov_b64 s[18:19], 0x4000000
	v_cndmask_b32_e32 v20, v18, v20, vcc
	v_lshlrev_b32_e32 v188, 2, v20
	v_xor_b32_e32 v20, 16, v18
	v_cmp_lt_i32_e32 vcc, v20, v19
	v_lshlrev_b32_e32 v191, 2, v26
	v_lshl_add_u64 v[180:181], v[28:29], 0, s[18:19]
	v_cndmask_b32_e32 v20, v18, v20, vcc
	v_lshlrev_b32_e32 v189, 2, v20
	v_xor_b32_e32 v20, 32, v18
	v_cmp_lt_i32_e32 vcc, v20, v19
	v_writelane_b32 v241, s24, 10
	s_add_i32 s28, s24, s84
	v_cndmask_b32_e32 v18, v18, v20, vcc
	v_lshlrev_b32_e32 v190, 2, v18
	v_lshl_add_u32 v18, v146, 7, 0
	v_add_u32_e32 v142, 0x11000, v18
	ds_read_b128 v[18:21], v142
	ds_read_b128 v[22:25], v142 offset:16
	ds_read_b128 v[26:29], v142 offset:32
	ds_read_b128 v[30:33], v142 offset:48
	ds_read_b128 v[34:37], v142 offset:64
	ds_read_b128 v[38:41], v142 offset:80
	ds_read_b128 v[42:45], v142 offset:96
	ds_read_b128 v[46:49], v142 offset:112
	ds_read_b128 v[50:53], v142 offset:8192
	ds_read_b128 v[54:57], v142 offset:8208
	ds_read_b128 v[58:61], v142 offset:8224
	ds_read_b128 v[62:65], v142 offset:8240
	ds_read_b128 v[66:69], v142 offset:8256
	ds_read_b128 v[70:73], v142 offset:8272
	ds_read_b128 v[74:77], v142 offset:8288
	ds_read_b128 v[78:81], v142 offset:8304
	ds_read_b128 v[82:85], v142 offset:16384
	ds_read_b128 v[86:89], v142 offset:16400
	ds_read_b128 v[90:93], v142 offset:16416
	ds_read_b128 v[94:97], v142 offset:16432
	ds_read_b128 v[98:101], v142 offset:16448
	ds_read_b128 v[102:105], v142 offset:16464
	ds_read_b128 v[106:109], v142 offset:16480
	ds_read_b128 v[110:113], v142 offset:16496
	ds_read_b128 v[114:117], v142 offset:24576
	ds_read_b128 v[118:121], v142 offset:24592
	ds_read_b128 v[122:125], v142 offset:24608
	ds_read_b128 v[126:129], v142 offset:24624
	ds_read_b128 v[130:133], v142 offset:24640
	ds_read_b128 v[134:137], v142 offset:24656
	ds_read_b128 v[138:141], v142 offset:24672
	ds_read_b128 v[142:145], v142 offset:24688
	v_cmp_gt_u32_e64 s[0:1], 8, v146
	v_cmp_eq_u32_e64 s[4:5], 7, v146
	v_cmp_eq_u32_e64 s[6:7], 6, v146
	v_cmp_eq_u32_e64 s[8:9], 5, v146
	v_cmp_eq_u32_e64 s[10:11], 4, v146
	v_cmp_eq_u32_e64 s[12:13], 3, v146
	v_cmp_eq_u32_e64 s[14:15], 2, v146
	v_cmp_eq_u32_e64 s[16:17], 1, v146
	s_lshl_b64 s[22:23], s[84:85], 11
	v_writelane_b32 v241, s25, 11
	s_ashr_i32 s29, s28, 31
	s_mov_b64 s[24:25], 0
	v_mov_b32_e32 v192, 0x358637bd
	s_mov_b32 s30, 0xf800000
	v_mov_b32_e32 v193, 0x260
	s_mov_b32 s31, 0xbfb8aa3b
	s_mov_b32 s33, 0xb2a5705f
	s_mov_b32 s34, 0x42ce8ed0
	s_mov_b32 s35, 0xc2b17218
	s_mov_b32 s36, 0x7f800000
	s_mov_b32 s37, 0x3f2aaaab
	v_mov_b32_e32 v194, 0x3ecc95a3
	s_mov_b32 s38, 0x3f317218
	s_mov_b32 s39, 0x33800000
	s_mov_b32 s40, 0x24100000
	v_lshlrev_b32_e32 v195, 2, v146
	v_mov_b32_e32 v196, 0x7f800000
	v_mov_b32_e32 v182, 0x3f317218
	s_waitcnt vmcnt(0)
	s_branch .LBB0_31

; __device__ __forceinline__ void phase0(const Params& P, LAS unsigned char* lds, int tid, int lane, int wave) {
;     ...
;     for (int m = gw; m < MT; m += NGW) {
;         f32x4 v[4]; float ss = 0.f;
; #pragma unroll
;         for (int j = 0; j < 4; ++j) { v[j] = nv[j]; ss += (v[j][0] * v[j][0] + v[j][1] * v[j][1]) + (v[j][2] * v[j][2] + v[j][3] * v[j][3]); }
;         if (m + NGW < MT) {
;             const int mn = m + NGW;
;             const float* xrow = (mn < MP) ? P.xp + (size_t)mn * 1024 : P.xs + (size_t)(mn - MP) * 1024;
; #pragma unroll
;             for (int j = 0; j < 4; ++j) nv[j] = *(const f32x4*)(xrow + 4 * lane + 256 * j);
;         }
.LBB0_31:
	s_add_i32 s41, s84, s3
	s_add_i32 s18, s41, 0x10000
	s_cmp_gt_i32 s18, 0x100ff
	s_cselect_b64 s[26:27], -1, 0
	s_cmp_lt_i32 s18, 0x10100
	v_mov_b32_e32 v146, v174
	v_mov_b32_e32 v147, v175
	v_mov_b32_e32 v148, v176
	v_mov_b32_e32 v149, v177
	v_mov_b32_e32 v150, v170
	v_mov_b32_e32 v151, v171
	v_mov_b32_e32 v152, v172
	v_mov_b32_e32 v153, v173
	v_mov_b32_e32 v154, v166
	v_mov_b32_e32 v155, v167
	v_mov_b32_e32 v156, v168
	v_mov_b32_e32 v157, v169
	v_mov_b32_e32 v158, v162
	v_mov_b32_e32 v159, v163
	v_mov_b32_e32 v160, v164
	v_mov_b32_e32 v161, v165
	s_cbranch_scc0 .LBB0_33
	s_add_u32 s42, s28, s24
	s_addc_u32 s19, s29, s25
	s_cmp_lt_i32 s18, 0x10000
	s_cselect_b32 s19, s19, 0
	s_cselect_b32 s18, s42, s41
	s_cselect_b32 s42, s69, s71
	s_cselect_b32 s43, s68, s70
	s_lshl_b64 s[18:19], s[18:19], 12
	s_add_u32 s18, s43, s18
	s_addc_u32 s19, s42, s19
	global_load_dwordx4 v[146:149], v191, s[18:19]
	global_load_dwordx4 v[150:153], v191, s[18:19] offset:1024
	global_load_dwordx4 v[154:157], v191, s[18:19] offset:2048
	global_load_dwordx4 v[158:161], v191, s[18:19] offset:3072

; __device__ __forceinline__ void phase4(const Params& P, int lane, int wave) {
;     ...
;     f32x4 g4[4];
; #pragma unroll
;     for (int j = 0; j < 4; ++j) g4[j] = *(const f32x4*)(P.fgain + 4 * lane + 256 * j);
;     f32x4 v[4]; u32x2 mv[4];
;     int m = gw;
;     if (m < MT) {
;         const float* xrow = (m < MP) ? P.xp + (size_t)m * 1024 : P.xs + (size_t)(m - MP) * 1024;
; #pragma unroll
;         for (int j = 0; j < 4; ++j) { v[j] = *(const f32x4*)(xrow + 4 * lane + 256 * j); mv[j] = *(const u32x2*)(mo + (size_t)m * 1024 + 4 * lane + 256 * j); }
;     }
.LBB0_798:
	v_readlane_b32 s20, v241, 10
	v_readlane_b32 s21, v241, 11
	s_lshl_b64 s[2:3], s[20:21], 11
	s_add_u32 s2, s4, s2
	s_addc_u32 s3, s5, s3
	v_lshlrev_b32_e32 v34, 1, v16
	v_lshlrev_b32_e32 v48, 2, v16
	global_load_dwordx2 v[54:55], v34, s[2:3] offset:1536
	global_load_dwordx2 v[56:57], v34, s[2:3] offset:1024
	global_load_dwordx2 v[58:59], v34, s[2:3] offset:512
	global_load_dwordx2 v[68:69], v34, s[2:3]
	global_load_dwordx4 v[28:31], v48, s[6:7]
	global_load_dwordx4 v[24:27], v48, s[6:7] offset:1024
	global_load_dwordx4 v[20:23], v48, s[6:7] offset:2048
	global_load_dwordx4 v[16:19], v48, s[6:7] offset:3072
	v_and_b32_e32 v33, 64, v32
	v_xor_b32_e32 v36, 1, v32
	v_add_u32_e32 v33, 64, v33
	v_mov_b32_e32 v35, 0
	v_xor_b32_e32 v37, 2, v32
	v_cmp_lt_i32_e32 vcc, v36, v33
	v_xor_b32_e32 v38, 4, v32
	v_lshl_add_u64 v[50:51], s[4:5], 0, v[34:35]
	v_cndmask_b32_e32 v34, v32, v36, vcc
	v_cmp_lt_i32_e32 vcc, v37, v33
	v_xor_b32_e32 v39, 8, v32
	v_mov_b32_e32 v49, v35
	v_cndmask_b32_e32 v35, v32, v37, vcc
	v_cmp_lt_i32_e32 vcc, v38, v33
	s_add_u32 s0, s90, s0
	v_xor_b32_e32 v40, 16, v32
	v_cndmask_b32_e32 v36, v32, v38, vcc
	v_cmp_lt_i32_e32 vcc, v39, v33
	s_addc_u32 s1, s91, s1
	s_add_i32 s4, s20, s84
	v_xor_b32_e32 v41, 32, v32
	v_cndmask_b32_e32 v37, v32, v39, vcc
	v_cmp_lt_i32_e32 vcc, v40, v33
	s_ashr_i32 s85, s84, 31
	s_ashr_i32 s5, s4, 31
	v_cndmask_b32_e32 v38, v32, v40, vcc
	v_cmp_lt_i32_e32 vcc, v41, v33
	v_lshl_add_u64 v[52:53], s[0:1], 0, v[48:49]
	s_lshl_b64 s[10:11], s[84:85], 12
	s_lshl_b64 s[0:1], s[4:5], 12
	v_cndmask_b32_e32 v32, v32, v41, vcc
	s_add_u32 s3, s68, s0
	s_mov_b64 s[6:7], 0
	s_mov_b32 s9, 0
	v_mov_b32_e32 v70, 0x358637bd
	s_mov_b32 s2, 0xf800000
	v_mov_b32_e32 v71, 0x260
	v_lshlrev_b32_e32 v72, 2, v34
	v_lshlrev_b32_e32 v73, 2, v35
	v_lshlrev_b32_e32 v74, 2, v36
	v_lshlrev_b32_e32 v75, 2, v37
	v_lshlrev_b32_e32 v76, 2, v38
	v_lshlrev_b32_e32 v77, 2, v32
	s_addc_u32 s18, s69, s1
	s_waitcnt vmcnt(7)
	v_mov_b64_e32 v[66:67], v[54:55]
	s_waitcnt vmcnt(6)
	v_mov_b64_e32 v[64:65], v[56:57]
	s_waitcnt vmcnt(5)
	v_mov_b64_e32 v[62:63], v[58:59]
	s_waitcnt vmcnt(4)
	v_mov_b64_e32 v[60:61], v[68:69]
	s_waitcnt vmcnt(0)
	s_branch .LBB0_801

; __device__ __forceinline__ float bf_lo(unsigned w) { return __uint_as_float(w << 16); }
; __device__ __forceinline__ float bf_hi(unsigned w) { return __uint_as_float(w & 0xffff0000u); }
; __device__ __forceinline__ void phase4(const Params& P, int lane, int wave) {
;     ...
;     for (; m < MT; m += NGW) {
;         f32x4 r[4]; float ss = 0.f;
; #pragma unroll
;         for (int j = 0; j < 4; ++j) {
;             r[j][0] = v[j][0] + bf_lo(mv[j].x); r[j][1] = v[j][1] + bf_hi(mv[j].x); r[j][2] = v[j][2] + bf_lo(mv[j].y); r[j][3] = v[j][3] + bf_hi(mv[j].y);
;             ss += (r[j][0] * r[j][0] + r[j][1] * r[j][1]) + (r[j][2] * r[j][2] + r[j][3] * r[j][3]);
;         }
;         const int mn = m + NGW;
;         if (mn < MT) {
;             const float* xrow = (mn < MP) ? P.xp + (size_t)mn * 1024 : P.xs + (size_t)(mn - MP) * 1024;
; #pragma unroll
;             for (int j = 0; j < 4; ++j) { v[j] = *(const f32x4*)(xrow + 4 * lane + 256 * j); mv[j] = *(const u32x2*)(mo + (size_t)mn * 1024 + 4 * lane + 256 * j); }
;         }
.LBB0_801:
	s_add_i32 s20, s20, s84
	s_cmp_gt_i32 s20, 0x100ff
	s_cselect_b64 s[12:13], -1, 0
	s_and_b64 vcc, exec, s[12:13]
	v_mov_b32_e32 v35, v19
	v_mov_b32_e32 v34, v18
	v_mov_b32_e32 v33, v17
	v_mov_b32_e32 v32, v16
	v_mov_b32_e32 v39, v23
	v_mov_b32_e32 v38, v22
	v_mov_b32_e32 v37, v21
	v_mov_b32_e32 v36, v20
	v_mov_b32_e32 v43, v27
	v_mov_b32_e32 v42, v26
	v_mov_b32_e32 v41, v25
	v_mov_b32_e32 v40, v24
	v_mov_b32_e32 v47, v31
	v_mov_b32_e32 v46, v30
	v_mov_b32_e32 v45, v29
	v_mov_b32_e32 v44, v28
	s_cbranch_vccnz .LBB0_800
	s_cmp_gt_i32 s20, 0xffff
	s_mov_b64 s[16:17], -1
	s_cbranch_scc0 .LBB0_804
	s_add_i32 s8, s20, 0xffff0000
	s_lshl_b64 s[0:1], s[8:9], 12
	s_add_u32 s0, s70, s0
	s_mov_b32 s21, s9
	s_addc_u32 s1, s71, s1
	s_mov_b64 s[16:17], 0
	s_mov_b64 s[14:15], s[20:21]
